# attention: compact max3 row-max + permlane32 swap instead of bpermute; K/V LDS stores moved into PV MFMA gaps
# speedup vs baseline: 1.0355x; 1.0111x over previous
; DI void attn_unit(LAS unsigned char* lds, const bf16_t* __restrict__ Q, const bf16_t* __restrict__ Kg, const bf16_t* __restrict__ VT, bf16_t* __restrict__ MIX, int b, int h, int c0, int nq, int desc) {
;     ...
;     if (do_cur && do_next && tau != 0) {
;       float mx = fmaxf(s0[0], s1[0]);
; #pragma unroll
;       for (int i = 1; i < 16; ++i) mx = fmaxf(mx, fmaxf(s0[i], s1[i]));
;       mx = fmaxf(mx, __shfl_xor(mx, 32));
;       const float mn = fmaxf(mrun, mx);
;       if (__builtin_amdgcn_ballot_w64(mn > mrun) != 0ull) {
;         const float alpha = __builtin_amdgcn_exp2f(mrun - mn); mrun = mn; lrun *= alpha;
; #pragma unroll
;         for (int d = 0; d < 4; ++d) O[d] = O[d] * alpha; }
.LBB0_548:
	v_max3_f32 v0, v82, v83, v84
	v_max3_f32 v99, v85, v86, v87
	v_max3_f32 v0, v0, v88, v89
	v_max3_f32 v99, v99, v90, v91
	v_max3_f32 v0, v0, v92, v93
	v_max3_f32 v99, v99, v94, v95
	v_max3_f32 v0, v0, v96, v97
	v_max3_f32 v99, v99, v66, v67
	v_max3_f32 v0, v0, v68, v69
	v_max3_f32 v99, v99, v70, v71
	v_max3_f32 v0, v0, v72, v73
	v_max3_f32 v99, v99, v74, v75
	v_max3_f32 v0, v0, v76, v77
	v_max3_f32 v99, v99, v78, v79
	v_max3_f32 v0, v0, v80, v81
	v_max_f32_e32 v0, v0, v99
	v_mov_b32_e32 v98, v0
	s_nop 1
	v_permlane32_swap_b32_e32 v0, v98
	v_max3_f32 v211, v122, v0, v98
	v_cmp_gt_f32_e32 vcc, v211, v122
	s_cbranch_vccz .LBB0_550
	v_sub_f32_e32 v0, v122, v211
	v_exp_f32_e32 v0, v0
	s_nop 0
	v_pk_mul_f32 v[64:65], v[64:65], v[0:1] op_sel_hi:[1,0]
	v_pk_mul_f32 v[62:63], v[62:63], v[0:1] op_sel_hi:[1,0]
	v_pk_mul_f32 v[60:61], v[60:61], v[0:1] op_sel_hi:[1,0]
	v_pk_mul_f32 v[58:59], v[58:59], v[0:1] op_sel_hi:[1,0]
	v_pk_mul_f32 v[56:57], v[56:57], v[0:1] op_sel_hi:[1,0]
	v_pk_mul_f32 v[54:55], v[54:55], v[0:1] op_sel_hi:[1,0]
	v_pk_mul_f32 v[52:53], v[52:53], v[0:1] op_sel_hi:[1,0]
	v_pk_mul_f32 v[50:51], v[50:51], v[0:1] op_sel_hi:[1,0]
	v_pk_mul_f32 v[48:49], v[48:49], v[0:1] op_sel_hi:[1,0]
	v_pk_mul_f32 v[46:47], v[46:47], v[0:1] op_sel_hi:[1,0]
	v_pk_mul_f32 v[44:45], v[44:45], v[0:1] op_sel_hi:[1,0]
	v_pk_mul_f32 v[42:43], v[42:43], v[0:1] op_sel_hi:[1,0]
	v_pk_mul_f32 v[40:41], v[40:41], v[0:1] op_sel_hi:[1,0]
	v_pk_mul_f32 v[38:39], v[38:39], v[0:1] op_sel_hi:[1,0]
	v_pk_mul_f32 v[36:37], v[36:37], v[0:1] op_sel_hi:[1,0]
	v_pk_mul_f32 v[34:35], v[34:35], v[0:1] op_sel_hi:[1,0]
	v_pk_mul_f32 v[32:33], v[32:33], v[0:1] op_sel_hi:[1,0]
	v_pk_mul_f32 v[30:31], v[30:31], v[0:1] op_sel_hi:[1,0]
	v_pk_mul_f32 v[28:29], v[28:29], v[0:1] op_sel_hi:[1,0]
	v_pk_mul_f32 v[26:27], v[26:27], v[0:1] op_sel_hi:[1,0]
	v_pk_mul_f32 v[24:25], v[24:25], v[0:1] op_sel_hi:[1,0]
	v_pk_mul_f32 v[22:23], v[22:23], v[0:1] op_sel_hi:[1,0]
	v_pk_mul_f32 v[20:21], v[20:21], v[0:1] op_sel_hi:[1,0]
	v_pk_mul_f32 v[18:19], v[18:19], v[0:1] op_sel_hi:[1,0]
	v_pk_mul_f32 v[16:17], v[16:17], v[0:1] op_sel_hi:[1,0]
	v_pk_mul_f32 v[14:15], v[14:15], v[0:1] op_sel_hi:[1,0]
	v_pk_mul_f32 v[12:13], v[12:13], v[0:1] op_sel_hi:[1,0]
	v_pk_mul_f32 v[10:11], v[10:11], v[0:1] op_sel_hi:[1,0]
	v_pk_mul_f32 v[8:9], v[8:9], v[0:1] op_sel_hi:[1,0]
	v_pk_mul_f32 v[6:7], v[6:7], v[0:1] op_sel_hi:[1,0]
	v_pk_mul_f32 v[4:5], v[4:5], v[0:1] op_sel_hi:[1,0]
	v_pk_mul_f32 v[2:3], v[2:3], v[0:1] op_sel_hi:[1,0]
	v_mul_f32_e32 v210, v210, v0
	s_branch .LBB0_551

; #define LAS __attribute__((address_space(3)))
; #define MFMA32(a, b, c) __builtin_amdgcn_mfma_f32_32x32x16_bf16((a), (b), (c), 0, 0, 0)
; DI int perm32k(int i) { return (i & 0x13) | ((i & 8) >> 1) | ((i & 4) << 1); }
; DI bf16x8 pack8(const f32x16& x, int s) { u32x4 p; p.x = pk2(x[8 * s], x[8 * s + 1]); p.y = pk2(x[8 * s + 2], x[8 * s + 3]); p.z = pk2(x[8 * s + 4], x[8 * s + 5]); p.w = pk2(x[8 * s + 6], x[8 * s + 7]); return __builtin_bit_cast(bf16x8, p); }
; DI void attn_unit(LAS unsigned char* lds, const bf16_t* __restrict__ Q, const bf16_t* __restrict__ Kg, const bf16_t* __restrict__ VT, bf16_t* __restrict__ MIX, int b, int h, int c0, int nq, int desc) {
;     ...
;       for (int i = 0; i < 16; ++i) { n0[i] = 0.f; n1[i] = 0.f; }
;       const LAS unsigned char* kb2 = lds + (buf ^ 1) * ATT_KB + perm32k(r31) * KROWB + 16 * hh;
;       __builtin_amdgcn_sched_barrier(0);
; #pragma unroll
;       for (int sx = 0; sx < 12; ++sx) { const bf16x8 a0 = *(const LAS bf16x8*)(kb2 + 32 * sx); const bf16x8 a1 = *(const LAS bf16x8*)(kb2 + 32 * KROWB + 32 * sx);
;         n0 = MFMA32(a0, qf[sx], n0); n1 = MFMA32(a1, qf[sx], n1);
; #pragma unroll
;         for (int j = 0; j < 3; ++j) { const int ei = 3 * sx + j; if (ei < 16) s0[ei] = __builtin_amdgcn_exp2f(s0[ei] - mrun); else if (ei < 32) s1[ei - 16] = __builtin_amdgcn_exp2f(s1[ei - 16] - mrun); }
;         __builtin_amdgcn_sched_barrier(0); }
;       float ps = 0.f;
; #pragma unroll
;       for (int i = 0; i < 16; ++i) ps += s0[i] + s1[i];
;       lrun += ps;
;       bf16x8 pf[4]; pf[0] = pack8(s0, 0); pf[1] = pack8(s0, 1); pf[2] = pack8(s1, 0); pf[3] = pack8(s1, 1);
.LBB0_551:
	s_xor_b32 s34, s12, 1
	s_mulk_i32 s34, 0x6400
	v_add_u32_e32 v223, s34, v208
	ds_read_b128 v[212:215], v223
	ds_read_b128 v[218:221], v223 offset:12800
	ds_read_b128 v[230:233], v223 offset:32
	ds_read_b128 v[234:237], v223 offset:12832
	v_sub_f32_e32 v82, v82, v211
	v_exp_f32_e32 v82, v82
	v_sub_f32_e32 v83, v83, v211
	v_exp_f32_e32 v83, v83
	v_sub_f32_e32 v84, v84, v211
	v_exp_f32_e32 v84, v84
	s_waitcnt lgkmcnt(3)
	v_mfma_f32_32x32x16_bf16 v[98:113], v[212:215], v[130:133], 0
	ds_read_b128 v[212:215], v223 offset:64
	v_sub_f32_e32 v85, v85, v211
	v_exp_f32_e32 v85, v85
	v_sub_f32_e32 v86, v86, v211
	v_exp_f32_e32 v86, v86
	s_waitcnt lgkmcnt(3)
	v_mfma_f32_32x32x16_bf16 v[114:129], v[218:221], v[130:133], 0
	ds_read_b128 v[218:221], v223 offset:12864
	v_sub_f32_e32 v87, v87, v211
	v_exp_f32_e32 v87, v87
	s_waitcnt lgkmcnt(3)
	v_mfma_f32_32x32x16_bf16 v[98:113], v[230:233], v[134:137], v[98:113]
	ds_read_b128 v[230:233], v223 offset:96
	v_sub_f32_e32 v88, v88, v211
	v_exp_f32_e32 v88, v88
	v_sub_f32_e32 v89, v89, v211
	v_exp_f32_e32 v89, v89
	s_waitcnt lgkmcnt(3)
	v_mfma_f32_32x32x16_bf16 v[114:129], v[234:237], v[134:137], v[114:129]
	ds_read_b128 v[234:237], v223 offset:12896
	v_sub_f32_e32 v90, v90, v211
	v_exp_f32_e32 v90, v90
	s_waitcnt lgkmcnt(3)
	v_mfma_f32_32x32x16_bf16 v[98:113], v[212:215], v[138:141], v[98:113]
	ds_read_b128 v[212:215], v223 offset:128
	v_sub_f32_e32 v91, v91, v211
	v_exp_f32_e32 v91, v91
	v_sub_f32_e32 v92, v92, v211
	v_exp_f32_e32 v92, v92
	s_waitcnt lgkmcnt(3)
	v_mfma_f32_32x32x16_bf16 v[114:129], v[218:221], v[138:141], v[114:129]
	ds_read_b128 v[218:221], v223 offset:12928
	v_sub_f32_e32 v93, v93, v211
	v_exp_f32_e32 v93, v93
	v_add_f32_e32 v238, v82, v86
	v_add_f32_e32 v239, v83, v87
	v_add_f32_e32 v240, v84, v88
	s_waitcnt lgkmcnt(3)
	v_mfma_f32_32x32x16_bf16 v[98:113], v[230:233], v[142:145], v[98:113]
	ds_read_b128 v[230:233], v223 offset:160
	v_sub_f32_e32 v94, v94, v211
	v_exp_f32_e32 v94, v94
	v_sub_f32_e32 v95, v95, v211
	v_exp_f32_e32 v95, v95
	s_waitcnt lgkmcnt(3)
	v_mfma_f32_32x32x16_bf16 v[114:129], v[234:237], v[142:145], v[114:129]
	ds_read_b128 v[234:237], v223 offset:12960
	v_sub_f32_e32 v96, v96, v211
	v_exp_f32_e32 v96, v96
	v_add_f32_e32 v241, v85, v89
	v_cvt_pk_bf16_f32 v82, v82, v83
	v_cvt_pk_bf16_f32 v83, v84, v85
	s_waitcnt lgkmcnt(3)
	v_mfma_f32_32x32x16_bf16 v[98:113], v[212:215], v[146:149], v[98:113]
	ds_read_b128 v[212:215], v223 offset:192
	v_sub_f32_e32 v97, v97, v211
	v_exp_f32_e32 v97, v97
	v_sub_f32_e32 v66, v66, v211
	v_exp_f32_e32 v66, v66
	s_waitcnt lgkmcnt(3)
	v_mfma_f32_32x32x16_bf16 v[114:129], v[218:221], v[146:149], v[114:129]
	ds_read_b128 v[218:221], v223 offset:12992
	v_sub_f32_e32 v67, v67, v211
	v_exp_f32_e32 v67, v67
	v_cvt_pk_bf16_f32 v84, v86, v87
	v_cvt_pk_bf16_f32 v85, v88, v89
	s_waitcnt lgkmcnt(3)
	v_mfma_f32_32x32x16_bf16 v[98:113], v[230:233], v[150:153], v[98:113]
	ds_read_b128 v[230:233], v223 offset:224
	v_sub_f32_e32 v68, v68, v211
	v_exp_f32_e32 v68, v68
	v_sub_f32_e32 v69, v69, v211
	v_exp_f32_e32 v69, v69
	s_waitcnt lgkmcnt(3)
	v_mfma_f32_32x32x16_bf16 v[114:129], v[234:237], v[150:153], v[114:129]
	ds_read_b128 v[234:237], v223 offset:13024
	v_sub_f32_e32 v70, v70, v211
	v_exp_f32_e32 v70, v70
	v_add_f32_e32 v238, v238, v90
	v_add_f32_e32 v239, v239, v91
	v_add_f32_e32 v240, v240, v92
	s_waitcnt lgkmcnt(3)
	v_mfma_f32_32x32x16_bf16 v[98:113], v[212:215], v[154:157], v[98:113]
	ds_read_b128 v[212:215], v223 offset:256
	v_sub_f32_e32 v71, v71, v211
	v_exp_f32_e32 v71, v71
	v_sub_f32_e32 v72, v72, v211
	v_exp_f32_e32 v72, v72
	s_waitcnt lgkmcnt(3)
	v_mfma_f32_32x32x16_bf16 v[114:129], v[218:221], v[154:157], v[114:129]
	ds_read_b128 v[218:221], v223 offset:13056
	v_sub_f32_e32 v73, v73, v211
	v_exp_f32_e32 v73, v73
	v_add_f32_e32 v241, v241, v93
	v_add_f32_e32 v238, v238, v94
	v_add_f32_e32 v239, v239, v95
	s_waitcnt lgkmcnt(3)
	v_mfma_f32_32x32x16_bf16 v[98:113], v[230:233], v[158:161], v[98:113]
	ds_read_b128 v[230:233], v223 offset:288
	v_sub_f32_e32 v74, v74, v211
	v_exp_f32_e32 v74, v74
	v_sub_f32_e32 v75, v75, v211
	v_exp_f32_e32 v75, v75
	s_waitcnt lgkmcnt(3)
	v_mfma_f32_32x32x16_bf16 v[114:129], v[234:237], v[158:161], v[114:129]
	ds_read_b128 v[234:237], v223 offset:13088
	v_sub_f32_e32 v76, v76, v211
	v_exp_f32_e32 v76, v76
	v_add_f32_e32 v240, v240, v96
	v_add_f32_e32 v241, v241, v97
	v_cvt_pk_bf16_f32 v90, v90, v91
	s_waitcnt lgkmcnt(3)
	v_mfma_f32_32x32x16_bf16 v[98:113], v[212:215], v[162:165], v[98:113]
	ds_read_b128 v[212:215], v223 offset:320
	v_sub_f32_e32 v77, v77, v211
	v_exp_f32_e32 v77, v77
	v_sub_f32_e32 v78, v78, v211
	v_exp_f32_e32 v78, v78
	s_waitcnt lgkmcnt(3)
	v_mfma_f32_32x32x16_bf16 v[114:129], v[218:221], v[162:165], v[114:129]
	ds_read_b128 v[218:221], v223 offset:13120
	v_sub_f32_e32 v79, v79, v211
	v_exp_f32_e32 v79, v79
	v_cvt_pk_bf16_f32 v91, v92, v93
	v_cvt_pk_bf16_f32 v92, v94, v95
	v_cvt_pk_bf16_f32 v93, v96, v97
	s_waitcnt lgkmcnt(3)
; #define LAS __attribute__((address_space(3)))
; #define MFMA32(a, b, c) __builtin_amdgcn_mfma_f32_32x32x16_bf16((a), (b), (c), 0, 0, 0)
; DI bf16x8 pack8(const f32x16& x, int s) { u32x4 p; p.x = pk2(x[8 * s], x[8 * s + 1]); p.y = pk2(x[8 * s + 2], x[8 * s + 3]); p.z = pk2(x[8 * s + 4], x[8 * s + 5]); p.w = pk2(x[8 * s + 6], x[8 * s + 7]); return __builtin_bit_cast(bf16x8, p); }
; #define ATT_STOREK(buf) do { _Pragma("unroll") for (int i = 0; i < 3; ++i) *(LAS u32x4*)(lds + (buf) * ATT_KB + klo + 128 * i) = kreg[i]; } while (0)
; #define ATT_STOREV(buf) do { _Pragma("unroll") for (int i = 0; i < 2; ++i) *(LAS u32x4*)(lds + (buf) * ATT_VB + vlo + 64 * i) = vreg[i]; } while (0)
; DI void attn_unit(LAS unsigned char* lds, const bf16_t* __restrict__ Q, const bf16_t* __restrict__ Kg, const bf16_t* __restrict__ VT, bf16_t* __restrict__ MIX, int b, int h, int c0, int nq, int desc) {
;     ...
;       for (int sx = 0; sx < 12; ++sx) { const bf16x8 a0 = *(const LAS bf16x8*)(kb2 + 32 * sx); const bf16x8 a1 = *(const LAS bf16x8*)(kb2 + 32 * KROWB + 32 * sx);
;         n0 = MFMA32(a0, qf[sx], n0); n1 = MFMA32(a1, qf[sx], n1);
; #pragma unroll
;         for (int j = 0; j < 3; ++j) { const int ei = 3 * sx + j; if (ei < 16) s0[ei] = __builtin_amdgcn_exp2f(s0[ei] - mrun); else if (ei < 32) s1[ei - 16] = __builtin_amdgcn_exp2f(s1[ei - 16] - mrun); }
;         __builtin_amdgcn_sched_barrier(0); }
;       float ps = 0.f;
; #pragma unroll
;       for (int i = 0; i < 16; ++i) ps += s0[i] + s1[i];
;       lrun += ps;
;       bf16x8 pf[4]; pf[0] = pack8(s0, 0); pf[1] = pack8(s0, 1); pf[2] = pack8(s1, 0); pf[3] = pack8(s1, 1);
;       const LAS unsigned char* vb = lds + 2 * ATT_KB + buf * ATT_VB + r31 * HROW + 16 * hh;
; #pragma unroll
;       for (int kk = 0; kk < 4; ++kk)
; #pragma unroll
;         for (int d = 0; d < 4; ++d) { const bf16x8 a = *(const LAS bf16x8*)(vb + d * 32 * HROW + 32 * kk); O[d] = MFMA32(a, pf[kk], O[d]); }
;     ...
;     if (t + 2 < nt) ATT_STOREK(buf);
;     if (t + 1 < nt) ATT_STOREV(buf ^ 1);
;     __syncthreads();
;     s0 = n0; s1 = n1;
	v_mfma_f32_32x32x16_bf16 v[98:113], v[230:233], v[166:169], v[98:113]
	ds_read_b128 v[230:233], v223 offset:352
	v_sub_f32_e32 v80, v80, v211
	v_exp_f32_e32 v80, v80
	v_sub_f32_e32 v81, v81, v211
	v_exp_f32_e32 v81, v81
	s_waitcnt lgkmcnt(3)
	v_mfma_f32_32x32x16_bf16 v[114:129], v[234:237], v[166:169], v[114:129]
	ds_read_b128 v[234:237], v223 offset:13152
	v_add_f32_e32 v238, v238, v66
	v_add_f32_e32 v239, v239, v67
	v_add_f32_e32 v240, v240, v68
	s_waitcnt lgkmcnt(3)
	v_mfma_f32_32x32x16_bf16 v[98:113], v[212:215], v[170:173], v[98:113]
	s_mul_i32 s34, s12, 0x4800
	v_add_u32_e32 v223, s34, v209
	ds_read_b128 v[212:215], v223 offset:51200
	v_add_f32_e32 v241, v241, v69
	v_add_f32_e32 v238, v238, v70
	v_add_f32_e32 v239, v239, v71
	s_waitcnt lgkmcnt(3)
	v_mfma_f32_32x32x16_bf16 v[114:129], v[218:221], v[170:173], v[114:129]
	ds_read_b128 v[218:221], v223 offset:55808
	v_add_f32_e32 v240, v240, v72
	v_add_f32_e32 v241, v241, v73
	v_cvt_pk_bf16_f32 v66, v66, v67
	s_waitcnt lgkmcnt(3)
	v_mfma_f32_32x32x16_bf16 v[98:113], v[230:233], v[174:177], v[98:113]
	ds_read_b128 v[230:233], v223 offset:60416
	v_cvt_pk_bf16_f32 v67, v68, v69
	v_cvt_pk_bf16_f32 v68, v70, v71
	v_cvt_pk_bf16_f32 v69, v72, v73
	s_waitcnt lgkmcnt(3)
	v_mfma_f32_32x32x16_bf16 v[114:129], v[234:237], v[174:177], v[114:129]
	ds_read_b128 v[234:237], v223 offset:65024
	v_add_f32_e32 v238, v238, v74
	v_add_f32_e32 v239, v239, v75
	v_add_f32_e32 v240, v240, v76
	s_waitcnt lgkmcnt(3)
	v_mfma_f32_32x32x16_bf16 v[50:65], v[212:215], v[82:85], v[50:65]
	ds_read_b128 v[212:215], v223 offset:51232
	v_add_f32_e32 v241, v241, v77
	v_add_f32_e32 v238, v238, v78
	v_add_f32_e32 v239, v239, v79
	s_waitcnt lgkmcnt(3)
	v_mfma_f32_32x32x16_bf16 v[34:49], v[218:221], v[82:85], v[34:49]
	ds_read_b128 v[218:221], v223 offset:55840
	v_add_f32_e32 v240, v240, v80
	v_add_f32_e32 v241, v241, v81
	v_cvt_pk_bf16_f32 v74, v74, v75
	s_waitcnt lgkmcnt(3)
	v_mfma_f32_32x32x16_bf16 v[18:33], v[230:233], v[82:85], v[18:33]
	ds_read_b128 v[230:233], v223 offset:60448
	v_cvt_pk_bf16_f32 v75, v76, v77
	v_cvt_pk_bf16_f32 v76, v78, v79
	v_cvt_pk_bf16_f32 v77, v80, v81
	s_andn2_b64 vcc, exec, s[26:27]
	s_cbranch_vccnz .Lnok_LBB0_551
	s_mul_i32 s98, s12, 0x6400
	v_add_u32_e32 v229, s98, v205
	s_waitcnt vmcnt(2)
	ds_write_b128 v229, v[178:181]
	ds_write_b128 v229, v[182:185] offset:128
	ds_write_b128 v229, v[186:189] offset:256
.Lnok_LBB0_551:
	s_waitcnt lgkmcnt(3)
	v_mfma_f32_32x32x16_bf16 v[2:17], v[234:237], v[82:85], v[2:17]
	ds_read_b128 v[234:237], v223 offset:65056
	v_add_f32_e32 v238, v238, v239
	v_add_f32_e32 v240, v240, v241
	s_waitcnt lgkmcnt(3)
	v_mfma_f32_32x32x16_bf16 v[50:65], v[212:215], v[90:93], v[50:65]
	ds_read_b128 v[212:215], v223 offset:51264
	v_add_f32_e32 v0, v238, v240
	s_waitcnt lgkmcnt(3)
	v_mfma_f32_32x32x16_bf16 v[34:49], v[218:221], v[90:93], v[34:49]
	ds_read_b128 v[218:221], v223 offset:55872
	v_add_f32_e32 v210, v210, v0
	s_waitcnt lgkmcnt(3)
	v_mfma_f32_32x32x16_bf16 v[18:33], v[230:233], v[90:93], v[18:33]
	ds_read_b128 v[230:233], v223 offset:60480
	s_xor_b32 s98, s12, 1
	s_mulk_i32 s98, 0x4800
	v_add_u32_e32 v229, s98, v206
	s_waitcnt vmcnt(0)
	ds_write_b128 v229, v[190:193] offset:51200
	ds_write_b128 v229, v[194:197] offset:51264
	s_waitcnt lgkmcnt(3)
	v_mfma_f32_32x32x16_bf16 v[2:17], v[234:237], v[90:93], v[2:17]
	ds_read_b128 v[234:237], v223 offset:65088
	s_waitcnt lgkmcnt(3)
	v_mfma_f32_32x32x16_bf16 v[50:65], v[212:215], v[66:69], v[50:65]
	ds_read_b128 v[212:215], v223 offset:51296
	s_waitcnt lgkmcnt(3)
	v_mfma_f32_32x32x16_bf16 v[34:49], v[218:221], v[66:69], v[34:49]
	ds_read_b128 v[218:221], v223 offset:55904
	s_waitcnt lgkmcnt(3)
	v_mfma_f32_32x32x16_bf16 v[18:33], v[230:233], v[66:69], v[18:33]
	ds_read_b128 v[230:233], v223 offset:60512
	s_waitcnt lgkmcnt(3)
	v_mfma_f32_32x32x16_bf16 v[2:17], v[234:237], v[66:69], v[2:17]
	ds_read_b128 v[234:237], v223 offset:65120
	s_waitcnt lgkmcnt(3)
	v_mfma_f32_32x32x16_bf16 v[50:65], v[212:215], v[74:77], v[50:65]
	s_waitcnt lgkmcnt(2)
	v_mfma_f32_32x32x16_bf16 v[34:49], v[218:221], v[74:77], v[34:49]
	s_waitcnt lgkmcnt(1)
	v_mfma_f32_32x32x16_bf16 v[18:33], v[230:233], v[74:77], v[18:33]
	s_waitcnt lgkmcnt(0)
	v_mfma_f32_32x32x16_bf16 v[2:17], v[234:237], v[74:77], v[2:17]
	v_mov_b64_e32 v[82:83], v[98:99]
	v_mov_b64_e32 v[66:67], v[114:115]
	v_mov_b64_e32 v[84:85], v[100:101]
	v_mov_b64_e32 v[86:87], v[102:103]
	v_mov_b64_e32 v[88:89], v[104:105]
	v_mov_b64_e32 v[90:91], v[106:107]
	v_mov_b64_e32 v[92:93], v[108:109]
	v_mov_b64_e32 v[94:95], v[110:111]
	v_mov_b64_e32 v[96:97], v[112:113]
	v_mov_b64_e32 v[68:69], v[116:117]
	v_mov_b64_e32 v[70:71], v[118:119]
	v_mov_b64_e32 v[72:73], v[120:121]
	v_mov_b64_e32 v[74:75], v[122:123]
	v_mov_b64_e32 v[76:77], v[124:125]
	v_mov_b64_e32 v[78:79], v[126:127]
	v_mov_b64_e32 v[80:81], v[128:129]
	s_or_b64 exec, exec, s[30:31]
	s_branch .LBB0_554
	s_andn2_b64 vcc, exec, s[26:27]
	s_cbranch_vccz .LBB0_560

; DI void attn_unit(LAS unsigned char* lds, const bf16_t* __restrict__ Q, const bf16_t* __restrict__ Kg, const bf16_t* __restrict__ VT, bf16_t* __restrict__ MIX, int b, int h, int c0, int nq, int desc) {
;     ...
;     if (do_cur && do_next && tau != 0) {
;       float mx = fmaxf(s0[0], s1[0]);
; #pragma unroll
;       for (int i = 1; i < 16; ++i) mx = fmaxf(mx, fmaxf(s0[i], s1[i]));
;       mx = fmaxf(mx, __shfl_xor(mx, 32));
;       const float mn = fmaxf(mrun, mx);
;       if (__builtin_amdgcn_ballot_w64(mn > mrun) != 0ull) {
;         const float alpha = __builtin_amdgcn_exp2f(mrun - mn); mrun = mn; lrun *= alpha;
; #pragma unroll
;         for (int d = 0; d < 4; ++d) O[d] = O[d] * alpha; }
.LBB0_580:
	v_max3_f32 v0, v112, v113, v114
	v_max3_f32 v3, v115, v116, v117
	v_max3_f32 v0, v0, v118, v119
	v_max3_f32 v3, v3, v120, v121
	v_max3_f32 v0, v0, v122, v123
	v_max3_f32 v3, v3, v124, v125
	v_max3_f32 v0, v0, v126, v127
	v_max3_f32 v3, v3, v96, v97
	v_max3_f32 v0, v0, v98, v99
	v_max3_f32 v3, v3, v100, v101
	v_max3_f32 v0, v0, v102, v103
	v_max3_f32 v3, v3, v104, v105
	v_max3_f32 v0, v0, v106, v107
	v_max3_f32 v3, v3, v108, v109
	v_max3_f32 v0, v0, v110, v111
	v_max_f32_e32 v0, v0, v3
	v_mov_b32_e32 v2, v0
	s_nop 1
	v_permlane32_swap_b32_e32 v0, v2
	v_max3_f32 v234, v94, v0, v2
	v_cmp_gt_f32_e32 vcc, v234, v94
	s_cbranch_vccz .LBB0_582
	v_sub_f32_e32 v0, v94, v234
	v_exp_f32_e32 v0, v0
	s_nop 0
	v_pk_mul_f32 v[78:79], v[78:79], v[0:1] op_sel_hi:[1,0]
	v_pk_mul_f32 v[76:77], v[76:77], v[0:1] op_sel_hi:[1,0]
	v_pk_mul_f32 v[74:75], v[74:75], v[0:1] op_sel_hi:[1,0]
	v_pk_mul_f32 v[72:73], v[72:73], v[0:1] op_sel_hi:[1,0]
	v_pk_mul_f32 v[70:71], v[70:71], v[0:1] op_sel_hi:[1,0]
	v_pk_mul_f32 v[68:69], v[68:69], v[0:1] op_sel_hi:[1,0]
	v_pk_mul_f32 v[66:67], v[66:67], v[0:1] op_sel_hi:[1,0]
	v_pk_mul_f32 v[64:65], v[64:65], v[0:1] op_sel_hi:[1,0]
	v_pk_mul_f32 v[62:63], v[62:63], v[0:1] op_sel_hi:[1,0]
	v_pk_mul_f32 v[60:61], v[60:61], v[0:1] op_sel_hi:[1,0]
	v_pk_mul_f32 v[58:59], v[58:59], v[0:1] op_sel_hi:[1,0]
	v_pk_mul_f32 v[56:57], v[56:57], v[0:1] op_sel_hi:[1,0]
	v_pk_mul_f32 v[54:55], v[54:55], v[0:1] op_sel_hi:[1,0]
	v_pk_mul_f32 v[52:53], v[52:53], v[0:1] op_sel_hi:[1,0]
	v_pk_mul_f32 v[50:51], v[50:51], v[0:1] op_sel_hi:[1,0]
	v_pk_mul_f32 v[48:49], v[48:49], v[0:1] op_sel_hi:[1,0]
	v_pk_mul_f32 v[46:47], v[46:47], v[0:1] op_sel_hi:[1,0]
	v_pk_mul_f32 v[44:45], v[44:45], v[0:1] op_sel_hi:[1,0]
	v_pk_mul_f32 v[42:43], v[42:43], v[0:1] op_sel_hi:[1,0]
	v_pk_mul_f32 v[40:41], v[40:41], v[0:1] op_sel_hi:[1,0]
	v_pk_mul_f32 v[38:39], v[38:39], v[0:1] op_sel_hi:[1,0]
	v_pk_mul_f32 v[36:37], v[36:37], v[0:1] op_sel_hi:[1,0]
	v_pk_mul_f32 v[34:35], v[34:35], v[0:1] op_sel_hi:[1,0]
	v_pk_mul_f32 v[32:33], v[32:33], v[0:1] op_sel_hi:[1,0]
	v_pk_mul_f32 v[30:31], v[30:31], v[0:1] op_sel_hi:[1,0]
	v_pk_mul_f32 v[28:29], v[28:29], v[0:1] op_sel_hi:[1,0]
	v_pk_mul_f32 v[26:27], v[26:27], v[0:1] op_sel_hi:[1,0]
	v_pk_mul_f32 v[24:25], v[24:25], v[0:1] op_sel_hi:[1,0]
	v_pk_mul_f32 v[22:23], v[22:23], v[0:1] op_sel_hi:[1,0]
	v_pk_mul_f32 v[20:21], v[20:21], v[0:1] op_sel_hi:[1,0]
	v_pk_mul_f32 v[18:19], v[18:19], v[0:1] op_sel_hi:[1,0]
	v_pk_mul_f32 v[16:17], v[16:17], v[0:1] op_sel_hi:[1,0]
	v_mul_f32_e32 v80, v80, v0
	s_branch .LBB0_583

; #define LAS __attribute__((address_space(3)))
; #define MFMA32(a, b, c) __builtin_amdgcn_mfma_f32_32x32x16_bf16((a), (b), (c), 0, 0, 0)
; DI int perm32k(int i) { return (i & 0x13) | ((i & 8) >> 1) | ((i & 4) << 1); }
; DI bf16x8 pack8(const f32x16& x, int s) { u32x4 p; p.x = pk2(x[8 * s], x[8 * s + 1]); p.y = pk2(x[8 * s + 2], x[8 * s + 3]); p.z = pk2(x[8 * s + 4], x[8 * s + 5]); p.w = pk2(x[8 * s + 6], x[8 * s + 7]); return __builtin_bit_cast(bf16x8, p); }
; DI void attn_unit(LAS unsigned char* lds, const bf16_t* __restrict__ Q, const bf16_t* __restrict__ Kg, const bf16_t* __restrict__ VT, bf16_t* __restrict__ MIX, int b, int h, int c0, int nq, int desc) {
;     ...
;       for (int i = 0; i < 16; ++i) { n0[i] = 0.f; n1[i] = 0.f; }
;       const LAS unsigned char* kb2 = lds + (buf ^ 1) * ATT_KB + perm32k(r31) * KROWB + 16 * hh;
;       __builtin_amdgcn_sched_barrier(0);
; #pragma unroll
;       for (int sx = 0; sx < 12; ++sx) { const bf16x8 a0 = *(const LAS bf16x8*)(kb2 + 32 * sx); const bf16x8 a1 = *(const LAS bf16x8*)(kb2 + 32 * KROWB + 32 * sx);
;         n0 = MFMA32(a0, qf[sx], n0); n1 = MFMA32(a1, qf[sx], n1);
; #pragma unroll
;         for (int j = 0; j < 3; ++j) { const int ei = 3 * sx + j; if (ei < 16) s0[ei] = __builtin_amdgcn_exp2f(s0[ei] - mrun); else if (ei < 32) s1[ei - 16] = __builtin_amdgcn_exp2f(s1[ei - 16] - mrun); }
;         __builtin_amdgcn_sched_barrier(0); }
;       float ps = 0.f;
; #pragma unroll
;       for (int i = 0; i < 16; ++i) ps += s0[i] + s1[i];
;       lrun += ps;
;       bf16x8 pf[4]; pf[0] = pack8(s0, 0); pf[1] = pack8(s0, 1); pf[2] = pack8(s1, 0); pf[3] = pack8(s1, 1);
.LBB0_583:
	s_xor_b32 s30, s71, 1
	s_mulk_i32 s30, 0x6400
	v_add_u32_e32 v95, s30, v81
	ds_read_b128 v[2:5], v95
	ds_read_b128 v[6:9], v95 offset:12800
	ds_read_b128 v[10:13], v95 offset:32
	ds_read_b128 v[236:239], v95 offset:12832
	v_sub_f32_e32 v112, v112, v234
	v_exp_f32_e32 v112, v112
	v_sub_f32_e32 v113, v113, v234
	v_exp_f32_e32 v113, v113
	v_sub_f32_e32 v114, v114, v234
	v_exp_f32_e32 v114, v114
	s_waitcnt lgkmcnt(3)
	v_mfma_f32_32x32x16_bf16 v[128:143], v[2:5], v[82:85], 0
	ds_read_b128 v[2:5], v95 offset:64
	v_sub_f32_e32 v115, v115, v234
	v_exp_f32_e32 v115, v115
	v_sub_f32_e32 v116, v116, v234
	v_exp_f32_e32 v116, v116
	s_waitcnt lgkmcnt(3)
	v_mfma_f32_32x32x16_bf16 v[144:159], v[6:9], v[82:85], 0
	ds_read_b128 v[6:9], v95 offset:12864
	v_sub_f32_e32 v117, v117, v234
	v_exp_f32_e32 v117, v117
	s_waitcnt lgkmcnt(3)
	v_mfma_f32_32x32x16_bf16 v[128:143], v[10:13], v[86:89], v[128:143]
	ds_read_b128 v[10:13], v95 offset:96
	v_sub_f32_e32 v118, v118, v234
	v_exp_f32_e32 v118, v118
	v_sub_f32_e32 v119, v119, v234
	v_exp_f32_e32 v119, v119
	s_waitcnt lgkmcnt(3)
	v_mfma_f32_32x32x16_bf16 v[144:159], v[236:239], v[86:89], v[144:159]
	ds_read_b128 v[236:239], v95 offset:12896
	v_sub_f32_e32 v120, v120, v234
	v_exp_f32_e32 v120, v120
	s_waitcnt lgkmcnt(3)
	v_mfma_f32_32x32x16_bf16 v[128:143], v[2:5], v[90:93], v[128:143]
	ds_read_b128 v[2:5], v95 offset:128
	v_sub_f32_e32 v121, v121, v234
	v_exp_f32_e32 v121, v121
	v_sub_f32_e32 v122, v122, v234
	v_exp_f32_e32 v122, v122
	s_waitcnt lgkmcnt(3)
	v_mfma_f32_32x32x16_bf16 v[144:159], v[6:9], v[90:93], v[144:159]
	ds_read_b128 v[6:9], v95 offset:12928
	v_sub_f32_e32 v123, v123, v234
	v_exp_f32_e32 v123, v123
	v_add_f32_e32 v14, v112, v116
	v_add_f32_e32 v15, v113, v117
	v_add_f32_e32 v240, v114, v118
	s_waitcnt lgkmcnt(3)
	v_mfma_f32_32x32x16_bf16 v[128:143], v[10:13], v[180:183], v[128:143]
	ds_read_b128 v[10:13], v95 offset:160
	v_sub_f32_e32 v124, v124, v234
	v_exp_f32_e32 v124, v124
	v_sub_f32_e32 v125, v125, v234
	v_exp_f32_e32 v125, v125
	s_waitcnt lgkmcnt(3)
	v_mfma_f32_32x32x16_bf16 v[144:159], v[236:239], v[180:183], v[144:159]
	ds_read_b128 v[236:239], v95 offset:12960
	v_sub_f32_e32 v126, v126, v234
	v_exp_f32_e32 v126, v126
	v_add_f32_e32 v241, v115, v119
	v_cvt_pk_bf16_f32 v112, v112, v113
	v_cvt_pk_bf16_f32 v113, v114, v115
	s_waitcnt lgkmcnt(3)
	v_mfma_f32_32x32x16_bf16 v[128:143], v[2:5], v[184:187], v[128:143]
	ds_read_b128 v[2:5], v95 offset:192
	v_sub_f32_e32 v127, v127, v234
	v_exp_f32_e32 v127, v127
	v_sub_f32_e32 v96, v96, v234
	v_exp_f32_e32 v96, v96
	s_waitcnt lgkmcnt(3)
	v_mfma_f32_32x32x16_bf16 v[144:159], v[6:9], v[184:187], v[144:159]
	ds_read_b128 v[6:9], v95 offset:12992
	v_sub_f32_e32 v97, v97, v234
	v_exp_f32_e32 v97, v97
	v_cvt_pk_bf16_f32 v114, v116, v117
	v_cvt_pk_bf16_f32 v115, v118, v119
	s_waitcnt lgkmcnt(3)
	v_mfma_f32_32x32x16_bf16 v[128:143], v[10:13], v[188:191], v[128:143]
	ds_read_b128 v[10:13], v95 offset:224
	v_sub_f32_e32 v98, v98, v234
	v_exp_f32_e32 v98, v98
	v_sub_f32_e32 v99, v99, v234
	v_exp_f32_e32 v99, v99
	s_waitcnt lgkmcnt(3)
	v_mfma_f32_32x32x16_bf16 v[144:159], v[236:239], v[188:191], v[144:159]
	ds_read_b128 v[236:239], v95 offset:13024
	v_sub_f32_e32 v100, v100, v234
	v_exp_f32_e32 v100, v100
	v_add_f32_e32 v14, v14, v120
	v_add_f32_e32 v15, v15, v121
	v_add_f32_e32 v240, v240, v122
	s_waitcnt lgkmcnt(3)
	v_mfma_f32_32x32x16_bf16 v[128:143], v[2:5], v[192:195], v[128:143]
	ds_read_b128 v[2:5], v95 offset:256
	v_sub_f32_e32 v101, v101, v234
	v_exp_f32_e32 v101, v101
	v_sub_f32_e32 v102, v102, v234
	v_exp_f32_e32 v102, v102
	s_waitcnt lgkmcnt(3)
	v_mfma_f32_32x32x16_bf16 v[144:159], v[6:9], v[192:195], v[144:159]
	ds_read_b128 v[6:9], v95 offset:13056
	v_sub_f32_e32 v103, v103, v234
	v_exp_f32_e32 v103, v103
	v_add_f32_e32 v241, v241, v123
	v_add_f32_e32 v14, v14, v124
	v_add_f32_e32 v15, v15, v125
	s_waitcnt lgkmcnt(3)
	v_mfma_f32_32x32x16_bf16 v[128:143], v[10:13], v[196:199], v[128:143]
	ds_read_b128 v[10:13], v95 offset:288
	v_sub_f32_e32 v104, v104, v234
	v_exp_f32_e32 v104, v104
	v_sub_f32_e32 v105, v105, v234
	v_exp_f32_e32 v105, v105
	s_waitcnt lgkmcnt(3)
	v_mfma_f32_32x32x16_bf16 v[144:159], v[236:239], v[196:199], v[144:159]
	ds_read_b128 v[236:239], v95 offset:13088
	v_sub_f32_e32 v106, v106, v234
	v_exp_f32_e32 v106, v106
	v_add_f32_e32 v240, v240, v126
	v_add_f32_e32 v241, v241, v127
	v_cvt_pk_bf16_f32 v120, v120, v121
	s_waitcnt lgkmcnt(3)
	v_mfma_f32_32x32x16_bf16 v[128:143], v[2:5], v[200:203], v[128:143]
	ds_read_b128 v[2:5], v95 offset:320
	v_sub_f32_e32 v107, v107, v234
	v_exp_f32_e32 v107, v107
	v_sub_f32_e32 v108, v108, v234
	v_exp_f32_e32 v108, v108
	s_waitcnt lgkmcnt(3)
; #define LAS __attribute__((address_space(3)))
; #define MFMA32(a, b, c) __builtin_amdgcn_mfma_f32_32x32x16_bf16((a), (b), (c), 0, 0, 0)
; DI bf16x8 pack8(const f32x16& x, int s) { u32x4 p; p.x = pk2(x[8 * s], x[8 * s + 1]); p.y = pk2(x[8 * s + 2], x[8 * s + 3]); p.z = pk2(x[8 * s + 4], x[8 * s + 5]); p.w = pk2(x[8 * s + 6], x[8 * s + 7]); return __builtin_bit_cast(bf16x8, p); }
; #define ATT_STOREK(buf) do { _Pragma("unroll") for (int i = 0; i < 3; ++i) *(LAS u32x4*)(lds + (buf) * ATT_KB + klo + 128 * i) = kreg[i]; } while (0)
; #define ATT_STOREV(buf) do { _Pragma("unroll") for (int i = 0; i < 2; ++i) *(LAS u32x4*)(lds + (buf) * ATT_VB + vlo + 64 * i) = vreg[i]; } while (0)
; DI void attn_unit(LAS unsigned char* lds, const bf16_t* __restrict__ Q, const bf16_t* __restrict__ Kg, const bf16_t* __restrict__ VT, bf16_t* __restrict__ MIX, int b, int h, int c0, int nq, int desc) {
;     ...
;       for (int sx = 0; sx < 12; ++sx) { const bf16x8 a0 = *(const LAS bf16x8*)(kb2 + 32 * sx); const bf16x8 a1 = *(const LAS bf16x8*)(kb2 + 32 * KROWB + 32 * sx);
;         n0 = MFMA32(a0, qf[sx], n0); n1 = MFMA32(a1, qf[sx], n1);
; #pragma unroll
;         for (int j = 0; j < 3; ++j) { const int ei = 3 * sx + j; if (ei < 16) s0[ei] = __builtin_amdgcn_exp2f(s0[ei] - mrun); else if (ei < 32) s1[ei - 16] = __builtin_amdgcn_exp2f(s1[ei - 16] - mrun); }
;         __builtin_amdgcn_sched_barrier(0); }
;       float ps = 0.f;
; #pragma unroll
;       for (int i = 0; i < 16; ++i) ps += s0[i] + s1[i];
;       lrun += ps;
;       bf16x8 pf[4]; pf[0] = pack8(s0, 0); pf[1] = pack8(s0, 1); pf[2] = pack8(s1, 0); pf[3] = pack8(s1, 1);
;       const LAS unsigned char* vb = lds + 2 * ATT_KB + buf * ATT_VB + r31 * HROW + 16 * hh;
; #pragma unroll
;       for (int kk = 0; kk < 4; ++kk)
; #pragma unroll
;         for (int d = 0; d < 4; ++d) { const bf16x8 a = *(const LAS bf16x8*)(vb + d * 32 * HROW + 32 * kk); O[d] = MFMA32(a, pf[kk], O[d]); }
;     ...
;     if (t + 2 < nt) ATT_STOREK(buf);
;     if (t + 1 < nt) ATT_STOREV(buf ^ 1);
	v_mfma_f32_32x32x16_bf16 v[144:159], v[6:9], v[200:203], v[144:159]
	ds_read_b128 v[6:9], v95 offset:13120
	v_sub_f32_e32 v109, v109, v234
	v_exp_f32_e32 v109, v109
	v_cvt_pk_bf16_f32 v121, v122, v123
	v_cvt_pk_bf16_f32 v122, v124, v125
	v_cvt_pk_bf16_f32 v123, v126, v127
	s_waitcnt lgkmcnt(3)
	v_mfma_f32_32x32x16_bf16 v[128:143], v[10:13], v[204:207], v[128:143]
	ds_read_b128 v[10:13], v95 offset:352
	v_sub_f32_e32 v110, v110, v234
	v_exp_f32_e32 v110, v110
	v_sub_f32_e32 v111, v111, v234
	v_exp_f32_e32 v111, v111
	s_waitcnt lgkmcnt(3)
	v_mfma_f32_32x32x16_bf16 v[144:159], v[236:239], v[204:207], v[144:159]
	ds_read_b128 v[236:239], v95 offset:13152
	v_add_f32_e32 v14, v14, v96
	v_add_f32_e32 v15, v15, v97
	v_add_f32_e32 v240, v240, v98
	s_waitcnt lgkmcnt(3)
	v_mfma_f32_32x32x16_bf16 v[128:143], v[2:5], v[208:211], v[128:143]
	s_mul_i32 s30, s71, 0x4800
	v_add_u32_e32 v95, s30, v232
	ds_read_b128 v[2:5], v95 offset:51200
	v_add_f32_e32 v241, v241, v99
	v_add_f32_e32 v14, v14, v100
	v_add_f32_e32 v15, v15, v101
	s_waitcnt lgkmcnt(3)
	v_mfma_f32_32x32x16_bf16 v[144:159], v[6:9], v[208:211], v[144:159]
	ds_read_b128 v[6:9], v95 offset:55808
	v_add_f32_e32 v240, v240, v102
	v_add_f32_e32 v241, v241, v103
	v_cvt_pk_bf16_f32 v96, v96, v97
	s_waitcnt lgkmcnt(3)
	v_mfma_f32_32x32x16_bf16 v[128:143], v[10:13], v[212:215], v[128:143]
	ds_read_b128 v[10:13], v95 offset:60416
	v_cvt_pk_bf16_f32 v97, v98, v99
	v_cvt_pk_bf16_f32 v98, v100, v101
	v_cvt_pk_bf16_f32 v99, v102, v103
	s_waitcnt lgkmcnt(3)
	v_mfma_f32_32x32x16_bf16 v[144:159], v[236:239], v[212:215], v[144:159]
	ds_read_b128 v[236:239], v95 offset:65024
	v_add_f32_e32 v14, v14, v104
	v_add_f32_e32 v15, v15, v105
	v_add_f32_e32 v240, v240, v106
	s_waitcnt lgkmcnt(3)
	v_mfma_f32_32x32x16_bf16 v[64:79], v[2:5], v[112:115], v[64:79]
	ds_read_b128 v[2:5], v95 offset:51232
	v_add_f32_e32 v241, v241, v107
	v_add_f32_e32 v14, v14, v108
	v_add_f32_e32 v15, v15, v109
	s_waitcnt lgkmcnt(3)
	v_mfma_f32_32x32x16_bf16 v[48:63], v[6:9], v[112:115], v[48:63]
	ds_read_b128 v[6:9], v95 offset:55840
	v_add_f32_e32 v240, v240, v110
	v_add_f32_e32 v241, v241, v111
	v_cvt_pk_bf16_f32 v104, v104, v105
	s_waitcnt lgkmcnt(3)
	v_mfma_f32_32x32x16_bf16 v[32:47], v[10:13], v[112:115], v[32:47]
	ds_read_b128 v[10:13], v95 offset:60448
	v_cvt_pk_bf16_f32 v105, v106, v107
	v_cvt_pk_bf16_f32 v106, v108, v109
	v_cvt_pk_bf16_f32 v107, v110, v111
	s_andn2_b64 vcc, exec, s[26:27]
	s_cbranch_vccnz .Lnok_LBB0_583
	s_mul_i32 s98, s71, 0x6400
	v_add_u32_e32 v235, s98, v231
	s_waitcnt vmcnt(2)
	ds_write_b128 v235, v[168:171]
	ds_write_b128 v235, v[172:175] offset:128
	ds_write_b128 v235, v[176:179] offset:256
.Lnok_LBB0_583:
	s_waitcnt lgkmcnt(3)
	v_mfma_f32_32x32x16_bf16 v[16:31], v[236:239], v[112:115], v[16:31]
	ds_read_b128 v[236:239], v95 offset:65056
	v_add_f32_e32 v14, v14, v15
	v_add_f32_e32 v240, v240, v241
	s_waitcnt lgkmcnt(3)
	v_mfma_f32_32x32x16_bf16 v[64:79], v[2:5], v[120:123], v[64:79]
	ds_read_b128 v[2:5], v95 offset:51264
	v_add_f32_e32 v0, v14, v240
	s_waitcnt lgkmcnt(3)
	v_mfma_f32_32x32x16_bf16 v[48:63], v[6:9], v[120:123], v[48:63]
	ds_read_b128 v[6:9], v95 offset:55872
	v_add_f32_e32 v80, v80, v0
	s_waitcnt lgkmcnt(3)
	v_mfma_f32_32x32x16_bf16 v[32:47], v[10:13], v[120:123], v[32:47]
	ds_read_b128 v[10:13], v95 offset:60480
	s_xor_b32 s98, s71, 1
	s_mulk_i32 s98, 0x4800
	v_add_u32_e32 v235, s98, v230
	s_waitcnt vmcnt(0)
	ds_write_b128 v235, v[160:163] offset:51200
	ds_write_b128 v235, v[164:167] offset:51264
	s_waitcnt lgkmcnt(3)
	v_mfma_f32_32x32x16_bf16 v[16:31], v[236:239], v[120:123], v[16:31]
	ds_read_b128 v[236:239], v95 offset:65088
	s_waitcnt lgkmcnt(3)
	v_mfma_f32_32x32x16_bf16 v[64:79], v[2:5], v[96:99], v[64:79]
	ds_read_b128 v[2:5], v95 offset:51296
	s_waitcnt lgkmcnt(3)
	v_mfma_f32_32x32x16_bf16 v[48:63], v[6:9], v[96:99], v[48:63]
	ds_read_b128 v[6:9], v95 offset:55904
	s_waitcnt lgkmcnt(3)
	v_mfma_f32_32x32x16_bf16 v[32:47], v[10:13], v[96:99], v[32:47]
	ds_read_b128 v[10:13], v95 offset:60512
	s_waitcnt lgkmcnt(3)
	v_mfma_f32_32x32x16_bf16 v[16:31], v[236:239], v[96:99], v[16:31]
	ds_read_b128 v[236:239], v95 offset:65120
	s_waitcnt lgkmcnt(3)
	v_mfma_f32_32x32x16_bf16 v[64:79], v[2:5], v[104:107], v[64:79]
	s_waitcnt lgkmcnt(2)
	v_mfma_f32_32x32x16_bf16 v[48:63], v[6:9], v[104:107], v[48:63]
	s_waitcnt lgkmcnt(1)
	v_mfma_f32_32x32x16_bf16 v[32:47], v[10:13], v[104:107], v[32:47]
	s_waitcnt lgkmcnt(0)
	v_mfma_f32_32x32x16_bf16 v[16:31], v[236:239], v[104:107], v[16:31]
	s_or_b64 exec, exec, s[6:7]
	s_branch .LBB0_586
	s_andn2_b64 vcc, exec, s[26:27]
	s_cbranch_vccz .LBB0_592

; #define LAS __attribute__((address_space(3)))
; #define MFMA32(a, b, c) __builtin_amdgcn_mfma_f32_32x32x16_bf16((a), (b), (c), 0, 0, 0)
; DI int perm32k(int i) { return (i & 0x13) | ((i & 8) >> 1) | ((i & 4) << 1); }
; DI bf16x8 pack8(const f32x16& x, int s) { u32x4 p; p.x = pk2(x[8 * s], x[8 * s + 1]); p.y = pk2(x[8 * s + 2], x[8 * s + 3]); p.z = pk2(x[8 * s + 4], x[8 * s + 5]); p.w = pk2(x[8 * s + 6], x[8 * s + 7]); return __builtin_bit_cast(bf16x8, p); }
; DI void attn_unit(LAS unsigned char* lds, const bf16_t* __restrict__ Q, const bf16_t* __restrict__ Kg, const bf16_t* __restrict__ VT, bf16_t* __restrict__ MIX, int b, int h, int c0, int nq, int desc) {
;     ...
;       for (int i = 0; i < 16; ++i) { n0[i] = 0.f; n1[i] = 0.f; }
;       const LAS unsigned char* kb2 = lds + (buf ^ 1) * ATT_KB + perm32k(r31) * KROWB + 16 * hh;
;       __builtin_amdgcn_sched_barrier(0);
; #pragma unroll
;       for (int sx = 0; sx < 12; ++sx) { const bf16x8 a0 = *(const LAS bf16x8*)(kb2 + 32 * sx); const bf16x8 a1 = *(const LAS bf16x8*)(kb2 + 32 * KROWB + 32 * sx);
;         n0 = MFMA32(a0, qf[sx], n0); n1 = MFMA32(a1, qf[sx], n1);
; #pragma unroll
;         for (int j = 0; j < 3; ++j) { const int ei = 3 * sx + j; if (ei < 16) s0[ei] = __builtin_amdgcn_exp2f(s0[ei] - mrun); else if (ei < 32) s1[ei - 16] = __builtin_amdgcn_exp2f(s1[ei - 16] - mrun); }
;         __builtin_amdgcn_sched_barrier(0); }
;       float ps = 0.f;
; #pragma unroll
;       for (int i = 0; i < 16; ++i) ps += s0[i] + s1[i];
;       lrun += ps;
;       bf16x8 pf[4]; pf[0] = pack8(s0, 0); pf[1] = pack8(s0, 1); pf[2] = pack8(s1, 0); pf[3] = pack8(s1, 1);
.LBB0_2562:
	s_xor_b32 s0, s12, 1
	s_mulk_i32 s0, 0x6400
	v_add_u32_e32 v223, s0, v208
	ds_read_b128 v[212:215], v223
	ds_read_b128 v[218:221], v223 offset:12800
	ds_read_b128 v[230:233], v223 offset:32
	ds_read_b128 v[234:237], v223 offset:12832
	v_sub_f32_e32 v82, v82, v211
	v_exp_f32_e32 v82, v82
	v_sub_f32_e32 v83, v83, v211
	v_exp_f32_e32 v83, v83
	v_sub_f32_e32 v84, v84, v211
	v_exp_f32_e32 v84, v84
	s_waitcnt lgkmcnt(3)
	v_mfma_f32_32x32x16_bf16 v[98:113], v[212:215], v[130:133], 0
	ds_read_b128 v[212:215], v223 offset:64
	v_sub_f32_e32 v85, v85, v211
	v_exp_f32_e32 v85, v85
	v_sub_f32_e32 v86, v86, v211
	v_exp_f32_e32 v86, v86
	s_waitcnt lgkmcnt(3)
	v_mfma_f32_32x32x16_bf16 v[114:129], v[218:221], v[130:133], 0
	ds_read_b128 v[218:221], v223 offset:12864
	v_sub_f32_e32 v87, v87, v211
	v_exp_f32_e32 v87, v87
	s_waitcnt lgkmcnt(3)
	v_mfma_f32_32x32x16_bf16 v[98:113], v[230:233], v[134:137], v[98:113]
	ds_read_b128 v[230:233], v223 offset:96
	v_sub_f32_e32 v88, v88, v211
	v_exp_f32_e32 v88, v88
	v_sub_f32_e32 v89, v89, v211
	v_exp_f32_e32 v89, v89
	s_waitcnt lgkmcnt(3)
	v_mfma_f32_32x32x16_bf16 v[114:129], v[234:237], v[134:137], v[114:129]
	ds_read_b128 v[234:237], v223 offset:12896
	v_sub_f32_e32 v90, v90, v211
	v_exp_f32_e32 v90, v90
	s_waitcnt lgkmcnt(3)
	v_mfma_f32_32x32x16_bf16 v[98:113], v[212:215], v[138:141], v[98:113]
	ds_read_b128 v[212:215], v223 offset:128
	v_sub_f32_e32 v91, v91, v211
	v_exp_f32_e32 v91, v91
	v_sub_f32_e32 v92, v92, v211
	v_exp_f32_e32 v92, v92
	s_waitcnt lgkmcnt(3)
	v_mfma_f32_32x32x16_bf16 v[114:129], v[218:221], v[138:141], v[114:129]
	ds_read_b128 v[218:221], v223 offset:12928
	v_sub_f32_e32 v93, v93, v211
	v_exp_f32_e32 v93, v93
	v_add_f32_e32 v238, v82, v86
	v_add_f32_e32 v239, v83, v87
	v_add_f32_e32 v240, v84, v88
	s_waitcnt lgkmcnt(3)
	v_mfma_f32_32x32x16_bf16 v[98:113], v[230:233], v[142:145], v[98:113]
	ds_read_b128 v[230:233], v223 offset:160
	v_sub_f32_e32 v94, v94, v211
	v_exp_f32_e32 v94, v94
	v_sub_f32_e32 v95, v95, v211
	v_exp_f32_e32 v95, v95
	s_waitcnt lgkmcnt(3)
	v_mfma_f32_32x32x16_bf16 v[114:129], v[234:237], v[142:145], v[114:129]
	ds_read_b128 v[234:237], v223 offset:12960
	v_sub_f32_e32 v96, v96, v211
	v_exp_f32_e32 v96, v96
	v_add_f32_e32 v241, v85, v89
	v_cvt_pk_bf16_f32 v82, v82, v83
	v_cvt_pk_bf16_f32 v83, v84, v85
	s_waitcnt lgkmcnt(3)
	v_mfma_f32_32x32x16_bf16 v[98:113], v[212:215], v[146:149], v[98:113]
	ds_read_b128 v[212:215], v223 offset:192
	v_sub_f32_e32 v97, v97, v211
	v_exp_f32_e32 v97, v97
	v_sub_f32_e32 v66, v66, v211
	v_exp_f32_e32 v66, v66
	s_waitcnt lgkmcnt(3)
	v_mfma_f32_32x32x16_bf16 v[114:129], v[218:221], v[146:149], v[114:129]
	ds_read_b128 v[218:221], v223 offset:12992
	v_sub_f32_e32 v67, v67, v211
	v_exp_f32_e32 v67, v67
	v_cvt_pk_bf16_f32 v84, v86, v87
	v_cvt_pk_bf16_f32 v85, v88, v89
	s_waitcnt lgkmcnt(3)
	v_mfma_f32_32x32x16_bf16 v[98:113], v[230:233], v[150:153], v[98:113]
	ds_read_b128 v[230:233], v223 offset:224
	v_sub_f32_e32 v68, v68, v211
	v_exp_f32_e32 v68, v68
	v_sub_f32_e32 v69, v69, v211
	v_exp_f32_e32 v69, v69
	s_waitcnt lgkmcnt(3)
	v_mfma_f32_32x32x16_bf16 v[114:129], v[234:237], v[150:153], v[114:129]
	ds_read_b128 v[234:237], v223 offset:13024
	v_sub_f32_e32 v70, v70, v211
	v_exp_f32_e32 v70, v70
	v_add_f32_e32 v238, v238, v90
	v_add_f32_e32 v239, v239, v91
	v_add_f32_e32 v240, v240, v92
	s_waitcnt lgkmcnt(3)
	v_mfma_f32_32x32x16_bf16 v[98:113], v[212:215], v[154:157], v[98:113]
	ds_read_b128 v[212:215], v223 offset:256
	v_sub_f32_e32 v71, v71, v211
	v_exp_f32_e32 v71, v71
	v_sub_f32_e32 v72, v72, v211
	v_exp_f32_e32 v72, v72
	s_waitcnt lgkmcnt(3)
; #define LAS __attribute__((address_space(3)))
; #define MFMA32(a, b, c) __builtin_amdgcn_mfma_f32_32x32x16_bf16((a), (b), (c), 0, 0, 0)
; DI bf16x8 pack8(const f32x16& x, int s) { u32x4 p; p.x = pk2(x[8 * s], x[8 * s + 1]); p.y = pk2(x[8 * s + 2], x[8 * s + 3]); p.z = pk2(x[8 * s + 4], x[8 * s + 5]); p.w = pk2(x[8 * s + 6], x[8 * s + 7]); return __builtin_bit_cast(bf16x8, p); }
; #define ATT_STOREK(buf) do { _Pragma("unroll") for (int i = 0; i < 3; ++i) *(LAS u32x4*)(lds + (buf) * ATT_KB + klo + 128 * i) = kreg[i]; } while (0)
; DI void attn_unit(LAS unsigned char* lds, const bf16_t* __restrict__ Q, const bf16_t* __restrict__ Kg, const bf16_t* __restrict__ VT, bf16_t* __restrict__ MIX, int b, int h, int c0, int nq, int desc) {
;     ...
;       for (int sx = 0; sx < 12; ++sx) { const bf16x8 a0 = *(const LAS bf16x8*)(kb2 + 32 * sx); const bf16x8 a1 = *(const LAS bf16x8*)(kb2 + 32 * KROWB + 32 * sx);
;         n0 = MFMA32(a0, qf[sx], n0); n1 = MFMA32(a1, qf[sx], n1);
; #pragma unroll
;         for (int j = 0; j < 3; ++j) { const int ei = 3 * sx + j; if (ei < 16) s0[ei] = __builtin_amdgcn_exp2f(s0[ei] - mrun); else if (ei < 32) s1[ei - 16] = __builtin_amdgcn_exp2f(s1[ei - 16] - mrun); }
;         __builtin_amdgcn_sched_barrier(0); }
;       float ps = 0.f;
; #pragma unroll
;       for (int i = 0; i < 16; ++i) ps += s0[i] + s1[i];
;       lrun += ps;
;       bf16x8 pf[4]; pf[0] = pack8(s0, 0); pf[1] = pack8(s0, 1); pf[2] = pack8(s1, 0); pf[3] = pack8(s1, 1);
;       const LAS unsigned char* vb = lds + 2 * ATT_KB + buf * ATT_VB + r31 * HROW + 16 * hh;
; #pragma unroll
;       for (int kk = 0; kk < 4; ++kk)
; #pragma unroll
;         for (int d = 0; d < 4; ++d) { const bf16x8 a = *(const LAS bf16x8*)(vb + d * 32 * HROW + 32 * kk); O[d] = MFMA32(a, pf[kk], O[d]); }
;     ...
;     if (t + 2 < nt) ATT_STOREK(buf);
	v_mfma_f32_32x32x16_bf16 v[114:129], v[218:221], v[154:157], v[114:129]
	ds_read_b128 v[218:221], v223 offset:13056
	v_sub_f32_e32 v73, v73, v211
	v_exp_f32_e32 v73, v73
	v_add_f32_e32 v241, v241, v93
	v_add_f32_e32 v238, v238, v94
	v_add_f32_e32 v239, v239, v95
	s_waitcnt lgkmcnt(3)
	v_mfma_f32_32x32x16_bf16 v[98:113], v[230:233], v[158:161], v[98:113]
	ds_read_b128 v[230:233], v223 offset:288
	v_sub_f32_e32 v74, v74, v211
	v_exp_f32_e32 v74, v74
	v_sub_f32_e32 v75, v75, v211
	v_exp_f32_e32 v75, v75
	s_waitcnt lgkmcnt(3)
	v_mfma_f32_32x32x16_bf16 v[114:129], v[234:237], v[158:161], v[114:129]
	ds_read_b128 v[234:237], v223 offset:13088
	v_sub_f32_e32 v76, v76, v211
	v_exp_f32_e32 v76, v76
	v_add_f32_e32 v240, v240, v96
	v_add_f32_e32 v241, v241, v97
	v_cvt_pk_bf16_f32 v90, v90, v91
	s_waitcnt lgkmcnt(3)
	v_mfma_f32_32x32x16_bf16 v[98:113], v[212:215], v[162:165], v[98:113]
	ds_read_b128 v[212:215], v223 offset:320
	v_sub_f32_e32 v77, v77, v211
	v_exp_f32_e32 v77, v77
	v_sub_f32_e32 v78, v78, v211
	v_exp_f32_e32 v78, v78
	s_waitcnt lgkmcnt(3)
	v_mfma_f32_32x32x16_bf16 v[114:129], v[218:221], v[162:165], v[114:129]
	ds_read_b128 v[218:221], v223 offset:13120
	v_sub_f32_e32 v79, v79, v211
	v_exp_f32_e32 v79, v79
	v_cvt_pk_bf16_f32 v91, v92, v93
	v_cvt_pk_bf16_f32 v92, v94, v95
	v_cvt_pk_bf16_f32 v93, v96, v97
	s_waitcnt lgkmcnt(3)
	v_mfma_f32_32x32x16_bf16 v[98:113], v[230:233], v[166:169], v[98:113]
	ds_read_b128 v[230:233], v223 offset:352
	v_sub_f32_e32 v80, v80, v211
	v_exp_f32_e32 v80, v80
	v_sub_f32_e32 v81, v81, v211
	v_exp_f32_e32 v81, v81
	s_waitcnt lgkmcnt(3)
	v_mfma_f32_32x32x16_bf16 v[114:129], v[234:237], v[166:169], v[114:129]
	ds_read_b128 v[234:237], v223 offset:13152
	v_add_f32_e32 v238, v238, v66
	v_add_f32_e32 v239, v239, v67
	v_add_f32_e32 v240, v240, v68
	s_waitcnt lgkmcnt(3)
	v_mfma_f32_32x32x16_bf16 v[98:113], v[212:215], v[170:173], v[98:113]
	s_mul_i32 s0, s12, 0x4800
	v_add_u32_e32 v223, s0, v209
	ds_read_b128 v[212:215], v223 offset:51200
	v_add_f32_e32 v241, v241, v69
	v_add_f32_e32 v238, v238, v70
	v_add_f32_e32 v239, v239, v71
	s_waitcnt lgkmcnt(3)
	v_mfma_f32_32x32x16_bf16 v[114:129], v[218:221], v[170:173], v[114:129]
	ds_read_b128 v[218:221], v223 offset:55808
	v_add_f32_e32 v240, v240, v72
	v_add_f32_e32 v241, v241, v73
	v_cvt_pk_bf16_f32 v66, v66, v67
	s_waitcnt lgkmcnt(3)
	v_mfma_f32_32x32x16_bf16 v[98:113], v[230:233], v[174:177], v[98:113]
	ds_read_b128 v[230:233], v223 offset:60416
	v_cvt_pk_bf16_f32 v67, v68, v69
	v_cvt_pk_bf16_f32 v68, v70, v71
	v_cvt_pk_bf16_f32 v69, v72, v73
	s_waitcnt lgkmcnt(3)
	v_mfma_f32_32x32x16_bf16 v[114:129], v[234:237], v[174:177], v[114:129]
	ds_read_b128 v[234:237], v223 offset:65024
	v_add_f32_e32 v238, v238, v74
	v_add_f32_e32 v239, v239, v75
	v_add_f32_e32 v240, v240, v76
	s_waitcnt lgkmcnt(3)
	v_mfma_f32_32x32x16_bf16 v[50:65], v[212:215], v[82:85], v[50:65]
	ds_read_b128 v[212:215], v223 offset:51232
	v_add_f32_e32 v241, v241, v77
	v_add_f32_e32 v238, v238, v78
	v_add_f32_e32 v239, v239, v79
	s_waitcnt lgkmcnt(3)
	v_mfma_f32_32x32x16_bf16 v[34:49], v[218:221], v[82:85], v[34:49]
	ds_read_b128 v[218:221], v223 offset:55840
	v_add_f32_e32 v240, v240, v80
	v_add_f32_e32 v241, v241, v81
	v_cvt_pk_bf16_f32 v74, v74, v75
	s_waitcnt lgkmcnt(3)
	v_mfma_f32_32x32x16_bf16 v[18:33], v[230:233], v[82:85], v[18:33]
	ds_read_b128 v[230:233], v223 offset:60448
	v_cvt_pk_bf16_f32 v75, v76, v77
	v_cvt_pk_bf16_f32 v76, v78, v79
	v_cvt_pk_bf16_f32 v77, v80, v81
	s_andn2_b64 vcc, exec, s[26:27]
	s_cbranch_vccnz .Lnok_LBB0_2562
	s_mul_i32 s98, s12, 0x6400
	v_add_u32_e32 v229, s98, v205
	s_waitcnt vmcnt(2)
	ds_write_b128 v229, v[178:181]
	ds_write_b128 v229, v[182:185] offset:128
	ds_write_b128 v229, v[186:189] offset:256

; DI void attn_unit(LAS unsigned char* lds, const bf16_t* __restrict__ Q, const bf16_t* __restrict__ Kg, const bf16_t* __restrict__ VT, bf16_t* __restrict__ MIX, int b, int h, int c0, int nq, int desc) {
;     ...
;     if (do_cur && do_next && tau != 0) {
;       float mx = fmaxf(s0[0], s1[0]);
; #pragma unroll
;       for (int i = 1; i < 16; ++i) mx = fmaxf(mx, fmaxf(s0[i], s1[i]));
;       mx = fmaxf(mx, __shfl_xor(mx, 32));
;       const float mn = fmaxf(mrun, mx);
;       if (__builtin_amdgcn_ballot_w64(mn > mrun) != 0ull) {
;         const float alpha = __builtin_amdgcn_exp2f(mrun - mn); mrun = mn; lrun *= alpha;
; #pragma unroll
;         for (int d = 0; d < 4; ++d) O[d] = O[d] * alpha; }
.LBB0_2591:
	v_max3_f32 v0, v112, v113, v114
	v_max3_f32 v3, v115, v116, v117
	v_max3_f32 v0, v0, v118, v119
	v_max3_f32 v3, v3, v120, v121
	v_max3_f32 v0, v0, v122, v123
	v_max3_f32 v3, v3, v124, v125
	v_max3_f32 v0, v0, v126, v127
	v_max3_f32 v3, v3, v96, v97
	v_max3_f32 v0, v0, v98, v99
	v_max3_f32 v3, v3, v100, v101
	v_max3_f32 v0, v0, v102, v103
	v_max3_f32 v3, v3, v104, v105
	v_max3_f32 v0, v0, v106, v107
	v_max3_f32 v3, v3, v108, v109
	v_max3_f32 v0, v0, v110, v111
	v_max_f32_e32 v0, v0, v3
	v_mov_b32_e32 v2, v0
	s_nop 1
	v_permlane32_swap_b32_e32 v0, v2
	v_max3_f32 v233, v94, v0, v2
	v_cmp_gt_f32_e32 vcc, v233, v94
	s_cbranch_vccz .LBB0_2593
	v_sub_f32_e32 v0, v94, v233
	v_exp_f32_e32 v0, v0
	s_nop 0
	v_pk_mul_f32 v[78:79], v[78:79], v[0:1] op_sel_hi:[1,0]
	v_pk_mul_f32 v[76:77], v[76:77], v[0:1] op_sel_hi:[1,0]
	v_pk_mul_f32 v[74:75], v[74:75], v[0:1] op_sel_hi:[1,0]
	v_pk_mul_f32 v[72:73], v[72:73], v[0:1] op_sel_hi:[1,0]
	v_pk_mul_f32 v[70:71], v[70:71], v[0:1] op_sel_hi:[1,0]
	v_pk_mul_f32 v[68:69], v[68:69], v[0:1] op_sel_hi:[1,0]
	v_pk_mul_f32 v[66:67], v[66:67], v[0:1] op_sel_hi:[1,0]
	v_pk_mul_f32 v[64:65], v[64:65], v[0:1] op_sel_hi:[1,0]
	v_pk_mul_f32 v[62:63], v[62:63], v[0:1] op_sel_hi:[1,0]
	v_pk_mul_f32 v[60:61], v[60:61], v[0:1] op_sel_hi:[1,0]
	v_pk_mul_f32 v[58:59], v[58:59], v[0:1] op_sel_hi:[1,0]
	v_pk_mul_f32 v[56:57], v[56:57], v[0:1] op_sel_hi:[1,0]
	v_pk_mul_f32 v[54:55], v[54:55], v[0:1] op_sel_hi:[1,0]
	v_pk_mul_f32 v[52:53], v[52:53], v[0:1] op_sel_hi:[1,0]
	v_pk_mul_f32 v[50:51], v[50:51], v[0:1] op_sel_hi:[1,0]
	v_pk_mul_f32 v[48:49], v[48:49], v[0:1] op_sel_hi:[1,0]
	v_pk_mul_f32 v[46:47], v[46:47], v[0:1] op_sel_hi:[1,0]
	v_pk_mul_f32 v[44:45], v[44:45], v[0:1] op_sel_hi:[1,0]
	v_pk_mul_f32 v[42:43], v[42:43], v[0:1] op_sel_hi:[1,0]
	v_pk_mul_f32 v[40:41], v[40:41], v[0:1] op_sel_hi:[1,0]
	v_pk_mul_f32 v[38:39], v[38:39], v[0:1] op_sel_hi:[1,0]
	v_pk_mul_f32 v[36:37], v[36:37], v[0:1] op_sel_hi:[1,0]
	v_pk_mul_f32 v[34:35], v[34:35], v[0:1] op_sel_hi:[1,0]
	v_pk_mul_f32 v[32:33], v[32:33], v[0:1] op_sel_hi:[1,0]
	v_pk_mul_f32 v[30:31], v[30:31], v[0:1] op_sel_hi:[1,0]
	v_pk_mul_f32 v[28:29], v[28:29], v[0:1] op_sel_hi:[1,0]
	v_pk_mul_f32 v[26:27], v[26:27], v[0:1] op_sel_hi:[1,0]
	v_pk_mul_f32 v[24:25], v[24:25], v[0:1] op_sel_hi:[1,0]
	v_pk_mul_f32 v[22:23], v[22:23], v[0:1] op_sel_hi:[1,0]
	v_pk_mul_f32 v[20:21], v[20:21], v[0:1] op_sel_hi:[1,0]
	v_pk_mul_f32 v[18:19], v[18:19], v[0:1] op_sel_hi:[1,0]
	v_pk_mul_f32 v[16:17], v[16:17], v[0:1] op_sel_hi:[1,0]
	v_mul_f32_e32 v80, v80, v0
	s_branch .LBB0_2594

; #define LAS __attribute__((address_space(3)))
; #define MFMA32(a, b, c) __builtin_amdgcn_mfma_f32_32x32x16_bf16((a), (b), (c), 0, 0, 0)
; DI int perm32k(int i) { return (i & 0x13) | ((i & 8) >> 1) | ((i & 4) << 1); }
; DI bf16x8 pack8(const f32x16& x, int s) { u32x4 p; p.x = pk2(x[8 * s], x[8 * s + 1]); p.y = pk2(x[8 * s + 2], x[8 * s + 3]); p.z = pk2(x[8 * s + 4], x[8 * s + 5]); p.w = pk2(x[8 * s + 6], x[8 * s + 7]); return __builtin_bit_cast(bf16x8, p); }
; DI void attn_unit(LAS unsigned char* lds, const bf16_t* __restrict__ Q, const bf16_t* __restrict__ Kg, const bf16_t* __restrict__ VT, bf16_t* __restrict__ MIX, int b, int h, int c0, int nq, int desc) {
;     ...
;       for (int i = 0; i < 16; ++i) { n0[i] = 0.f; n1[i] = 0.f; }
;       const LAS unsigned char* kb2 = lds + (buf ^ 1) * ATT_KB + perm32k(r31) * KROWB + 16 * hh;
;       __builtin_amdgcn_sched_barrier(0);
; #pragma unroll
;       for (int sx = 0; sx < 12; ++sx) { const bf16x8 a0 = *(const LAS bf16x8*)(kb2 + 32 * sx); const bf16x8 a1 = *(const LAS bf16x8*)(kb2 + 32 * KROWB + 32 * sx);
;         n0 = MFMA32(a0, qf[sx], n0); n1 = MFMA32(a1, qf[sx], n1);
; #pragma unroll
;         for (int j = 0; j < 3; ++j) { const int ei = 3 * sx + j; if (ei < 16) s0[ei] = __builtin_amdgcn_exp2f(s0[ei] - mrun); else if (ei < 32) s1[ei - 16] = __builtin_amdgcn_exp2f(s1[ei - 16] - mrun); }
;         __builtin_amdgcn_sched_barrier(0); }
;       float ps = 0.f;
; #pragma unroll
;       for (int i = 0; i < 16; ++i) ps += s0[i] + s1[i];
;       lrun += ps;
;       bf16x8 pf[4]; pf[0] = pack8(s0, 0); pf[1] = pack8(s0, 1); pf[2] = pack8(s1, 0); pf[3] = pack8(s1, 1);
.LBB0_2594:
	s_xor_b32 s0, s71, 1
	s_mulk_i32 s0, 0x6400
	v_add_u32_e32 v95, s0, v81
	ds_read_b128 v[2:5], v95
	ds_read_b128 v[6:9], v95 offset:12800
	ds_read_b128 v[10:13], v95 offset:32
	ds_read_b128 v[236:239], v95 offset:12832
	v_sub_f32_e32 v112, v112, v233
	v_exp_f32_e32 v112, v112
	v_sub_f32_e32 v113, v113, v233
	v_exp_f32_e32 v113, v113
	v_sub_f32_e32 v114, v114, v233
	v_exp_f32_e32 v114, v114
	s_waitcnt lgkmcnt(3)
	v_mfma_f32_32x32x16_bf16 v[128:143], v[2:5], v[82:85], 0
	ds_read_b128 v[2:5], v95 offset:64
	v_sub_f32_e32 v115, v115, v233
	v_exp_f32_e32 v115, v115
	v_sub_f32_e32 v116, v116, v233
	v_exp_f32_e32 v116, v116
	s_waitcnt lgkmcnt(3)
	v_mfma_f32_32x32x16_bf16 v[144:159], v[6:9], v[82:85], 0
	ds_read_b128 v[6:9], v95 offset:12864
	v_sub_f32_e32 v117, v117, v233
	v_exp_f32_e32 v117, v117
	s_waitcnt lgkmcnt(3)
	v_mfma_f32_32x32x16_bf16 v[128:143], v[10:13], v[86:89], v[128:143]
	ds_read_b128 v[10:13], v95 offset:96
	v_sub_f32_e32 v118, v118, v233
	v_exp_f32_e32 v118, v118
	v_sub_f32_e32 v119, v119, v233
	v_exp_f32_e32 v119, v119
	s_waitcnt lgkmcnt(3)
	v_mfma_f32_32x32x16_bf16 v[144:159], v[236:239], v[86:89], v[144:159]
	ds_read_b128 v[236:239], v95 offset:12896
	v_sub_f32_e32 v120, v120, v233
	v_exp_f32_e32 v120, v120
	s_waitcnt lgkmcnt(3)
	v_mfma_f32_32x32x16_bf16 v[128:143], v[2:5], v[90:93], v[128:143]
	ds_read_b128 v[2:5], v95 offset:128
	v_sub_f32_e32 v121, v121, v233
	v_exp_f32_e32 v121, v121
	v_sub_f32_e32 v122, v122, v233
	v_exp_f32_e32 v122, v122
	s_waitcnt lgkmcnt(3)
	v_mfma_f32_32x32x16_bf16 v[144:159], v[6:9], v[90:93], v[144:159]
	ds_read_b128 v[6:9], v95 offset:12928
	v_sub_f32_e32 v123, v123, v233
	v_exp_f32_e32 v123, v123
	v_add_f32_e32 v14, v112, v116
	v_add_f32_e32 v15, v113, v117
	v_add_f32_e32 v240, v114, v118
	s_waitcnt lgkmcnt(3)
	v_mfma_f32_32x32x16_bf16 v[128:143], v[10:13], v[180:183], v[128:143]
	ds_read_b128 v[10:13], v95 offset:160
	v_sub_f32_e32 v124, v124, v233
	v_exp_f32_e32 v124, v124
	v_sub_f32_e32 v125, v125, v233
	v_exp_f32_e32 v125, v125
	s_waitcnt lgkmcnt(3)
	v_mfma_f32_32x32x16_bf16 v[144:159], v[236:239], v[180:183], v[144:159]
	ds_read_b128 v[236:239], v95 offset:12960
	v_sub_f32_e32 v126, v126, v233
	v_exp_f32_e32 v126, v126
	v_add_f32_e32 v241, v115, v119
	v_cvt_pk_bf16_f32 v112, v112, v113
	v_cvt_pk_bf16_f32 v113, v114, v115
	s_waitcnt lgkmcnt(3)
	v_mfma_f32_32x32x16_bf16 v[128:143], v[2:5], v[184:187], v[128:143]
	ds_read_b128 v[2:5], v95 offset:192
	v_sub_f32_e32 v127, v127, v233
	v_exp_f32_e32 v127, v127
	v_sub_f32_e32 v96, v96, v233
	v_exp_f32_e32 v96, v96
	s_waitcnt lgkmcnt(3)
	v_mfma_f32_32x32x16_bf16 v[144:159], v[6:9], v[184:187], v[144:159]
	ds_read_b128 v[6:9], v95 offset:12992
	v_sub_f32_e32 v97, v97, v233
	v_exp_f32_e32 v97, v97
	v_cvt_pk_bf16_f32 v114, v116, v117
	v_cvt_pk_bf16_f32 v115, v118, v119
	s_waitcnt lgkmcnt(3)
	v_mfma_f32_32x32x16_bf16 v[128:143], v[10:13], v[188:191], v[128:143]
	ds_read_b128 v[10:13], v95 offset:224
	v_sub_f32_e32 v98, v98, v233
	v_exp_f32_e32 v98, v98
	v_sub_f32_e32 v99, v99, v233
	v_exp_f32_e32 v99, v99
	s_waitcnt lgkmcnt(3)
	v_mfma_f32_32x32x16_bf16 v[144:159], v[236:239], v[188:191], v[144:159]
	ds_read_b128 v[236:239], v95 offset:13024
	v_sub_f32_e32 v100, v100, v233
	v_exp_f32_e32 v100, v100
	v_add_f32_e32 v14, v14, v120
	v_add_f32_e32 v15, v15, v121
	v_add_f32_e32 v240, v240, v122
	s_waitcnt lgkmcnt(3)
	v_mfma_f32_32x32x16_bf16 v[128:143], v[2:5], v[192:195], v[128:143]
	ds_read_b128 v[2:5], v95 offset:256
	v_sub_f32_e32 v101, v101, v233
	v_exp_f32_e32 v101, v101
	v_sub_f32_e32 v102, v102, v233
	v_exp_f32_e32 v102, v102
	s_waitcnt lgkmcnt(3)
	v_mfma_f32_32x32x16_bf16 v[144:159], v[6:9], v[192:195], v[144:159]
	ds_read_b128 v[6:9], v95 offset:13056
	v_sub_f32_e32 v103, v103, v233
	v_exp_f32_e32 v103, v103
	v_add_f32_e32 v241, v241, v123
	v_add_f32_e32 v14, v14, v124
	v_add_f32_e32 v15, v15, v125
	s_waitcnt lgkmcnt(3)
	v_mfma_f32_32x32x16_bf16 v[128:143], v[10:13], v[196:199], v[128:143]
	ds_read_b128 v[10:13], v95 offset:288
	v_sub_f32_e32 v104, v104, v233
	v_exp_f32_e32 v104, v104
	v_sub_f32_e32 v105, v105, v233
	v_exp_f32_e32 v105, v105
	s_waitcnt lgkmcnt(3)
	v_mfma_f32_32x32x16_bf16 v[144:159], v[236:239], v[196:199], v[144:159]
	ds_read_b128 v[236:239], v95 offset:13088
	v_sub_f32_e32 v106, v106, v233
	v_exp_f32_e32 v106, v106
	v_add_f32_e32 v240, v240, v126
	v_add_f32_e32 v241, v241, v127
	v_cvt_pk_bf16_f32 v120, v120, v121
	s_waitcnt lgkmcnt(3)
	v_mfma_f32_32x32x16_bf16 v[128:143], v[2:5], v[200:203], v[128:143]
	ds_read_b128 v[2:5], v95 offset:320
	v_sub_f32_e32 v107, v107, v233
	v_exp_f32_e32 v107, v107
	v_sub_f32_e32 v108, v108, v233
	v_exp_f32_e32 v108, v108
	s_waitcnt lgkmcnt(3)
; #define LAS __attribute__((address_space(3)))
; #define MFMA32(a, b, c) __builtin_amdgcn_mfma_f32_32x32x16_bf16((a), (b), (c), 0, 0, 0)
; DI bf16x8 pack8(const f32x16& x, int s) { u32x4 p; p.x = pk2(x[8 * s], x[8 * s + 1]); p.y = pk2(x[8 * s + 2], x[8 * s + 3]); p.z = pk2(x[8 * s + 4], x[8 * s + 5]); p.w = pk2(x[8 * s + 6], x[8 * s + 7]); return __builtin_bit_cast(bf16x8, p); }
; #define ATT_STOREK(buf) do { _Pragma("unroll") for (int i = 0; i < 3; ++i) *(LAS u32x4*)(lds + (buf) * ATT_KB + klo + 128 * i) = kreg[i]; } while (0)
; #define ATT_STOREV(buf) do { _Pragma("unroll") for (int i = 0; i < 2; ++i) *(LAS u32x4*)(lds + (buf) * ATT_VB + vlo + 64 * i) = vreg[i]; } while (0)
; DI void attn_unit(LAS unsigned char* lds, const bf16_t* __restrict__ Q, const bf16_t* __restrict__ Kg, const bf16_t* __restrict__ VT, bf16_t* __restrict__ MIX, int b, int h, int c0, int nq, int desc) {
;     ...
;       for (int sx = 0; sx < 12; ++sx) { const bf16x8 a0 = *(const LAS bf16x8*)(kb2 + 32 * sx); const bf16x8 a1 = *(const LAS bf16x8*)(kb2 + 32 * KROWB + 32 * sx);
;         n0 = MFMA32(a0, qf[sx], n0); n1 = MFMA32(a1, qf[sx], n1);
; #pragma unroll
;         for (int j = 0; j < 3; ++j) { const int ei = 3 * sx + j; if (ei < 16) s0[ei] = __builtin_amdgcn_exp2f(s0[ei] - mrun); else if (ei < 32) s1[ei - 16] = __builtin_amdgcn_exp2f(s1[ei - 16] - mrun); }
;         __builtin_amdgcn_sched_barrier(0); }
;       float ps = 0.f;
; #pragma unroll
;       for (int i = 0; i < 16; ++i) ps += s0[i] + s1[i];
;       lrun += ps;
;       bf16x8 pf[4]; pf[0] = pack8(s0, 0); pf[1] = pack8(s0, 1); pf[2] = pack8(s1, 0); pf[3] = pack8(s1, 1);
;       const LAS unsigned char* vb = lds + 2 * ATT_KB + buf * ATT_VB + r31 * HROW + 16 * hh;
; #pragma unroll
;       for (int kk = 0; kk < 4; ++kk)
; #pragma unroll
;         for (int d = 0; d < 4; ++d) { const bf16x8 a = *(const LAS bf16x8*)(vb + d * 32 * HROW + 32 * kk); O[d] = MFMA32(a, pf[kk], O[d]); }
;     ...
;     if (t + 2 < nt) ATT_STOREK(buf);
;     if (t + 1 < nt) ATT_STOREV(buf ^ 1);
	v_mfma_f32_32x32x16_bf16 v[144:159], v[6:9], v[200:203], v[144:159]
	ds_read_b128 v[6:9], v95 offset:13120
	v_sub_f32_e32 v109, v109, v233
	v_exp_f32_e32 v109, v109
	v_cvt_pk_bf16_f32 v121, v122, v123
	v_cvt_pk_bf16_f32 v122, v124, v125
	v_cvt_pk_bf16_f32 v123, v126, v127
	s_waitcnt lgkmcnt(3)
	v_mfma_f32_32x32x16_bf16 v[128:143], v[10:13], v[204:207], v[128:143]
	ds_read_b128 v[10:13], v95 offset:352
	v_sub_f32_e32 v110, v110, v233
	v_exp_f32_e32 v110, v110
	v_sub_f32_e32 v111, v111, v233
	v_exp_f32_e32 v111, v111
	s_waitcnt lgkmcnt(3)
	v_mfma_f32_32x32x16_bf16 v[144:159], v[236:239], v[204:207], v[144:159]
	ds_read_b128 v[236:239], v95 offset:13152
	v_add_f32_e32 v14, v14, v96
	v_add_f32_e32 v15, v15, v97
	v_add_f32_e32 v240, v240, v98
	s_waitcnt lgkmcnt(3)
	v_mfma_f32_32x32x16_bf16 v[128:143], v[2:5], v[208:211], v[128:143]
	s_mul_i32 s0, s71, 0x4800
	v_add_u32_e32 v95, s0, v231
	ds_read_b128 v[2:5], v95 offset:51200
	v_add_f32_e32 v241, v241, v99
	v_add_f32_e32 v14, v14, v100
	v_add_f32_e32 v15, v15, v101
	s_waitcnt lgkmcnt(3)
	v_mfma_f32_32x32x16_bf16 v[144:159], v[6:9], v[208:211], v[144:159]
	ds_read_b128 v[6:9], v95 offset:55808
	v_add_f32_e32 v240, v240, v102
	v_add_f32_e32 v241, v241, v103
	v_cvt_pk_bf16_f32 v96, v96, v97
	s_waitcnt lgkmcnt(3)
	v_mfma_f32_32x32x16_bf16 v[128:143], v[10:13], v[212:215], v[128:143]
	ds_read_b128 v[10:13], v95 offset:60416
	v_cvt_pk_bf16_f32 v97, v98, v99
	v_cvt_pk_bf16_f32 v98, v100, v101
	v_cvt_pk_bf16_f32 v99, v102, v103
	s_waitcnt lgkmcnt(3)
	v_mfma_f32_32x32x16_bf16 v[144:159], v[236:239], v[212:215], v[144:159]
	ds_read_b128 v[236:239], v95 offset:65024
	v_add_f32_e32 v14, v14, v104
	v_add_f32_e32 v15, v15, v105
	v_add_f32_e32 v240, v240, v106
	s_waitcnt lgkmcnt(3)
	v_mfma_f32_32x32x16_bf16 v[64:79], v[2:5], v[112:115], v[64:79]
	ds_read_b128 v[2:5], v95 offset:51232
	v_add_f32_e32 v241, v241, v107
	v_add_f32_e32 v14, v14, v108
	v_add_f32_e32 v15, v15, v109
	s_waitcnt lgkmcnt(3)
	v_mfma_f32_32x32x16_bf16 v[48:63], v[6:9], v[112:115], v[48:63]
	ds_read_b128 v[6:9], v95 offset:55840
	v_add_f32_e32 v240, v240, v110
	v_add_f32_e32 v241, v241, v111
	v_cvt_pk_bf16_f32 v104, v104, v105
	s_waitcnt lgkmcnt(3)
	v_mfma_f32_32x32x16_bf16 v[32:47], v[10:13], v[112:115], v[32:47]
	ds_read_b128 v[10:13], v95 offset:60448
	v_cvt_pk_bf16_f32 v105, v106, v107
	v_cvt_pk_bf16_f32 v106, v108, v109
	v_cvt_pk_bf16_f32 v107, v110, v111
	s_andn2_b64 vcc, exec, s[26:27]
	s_cbranch_vccnz .Lnok_LBB0_2594
	s_mul_i32 s98, s71, 0x6400
	v_add_u32_e32 v235, s98, v230
	s_waitcnt vmcnt(2)
	ds_write_b128 v235, v[168:171]
	ds_write_b128 v235, v[172:175] offset:128
	ds_write_b128 v235, v[176:179] offset:256
.Lnok_LBB0_2594:
	s_waitcnt lgkmcnt(3)
	v_mfma_f32_32x32x16_bf16 v[16:31], v[236:239], v[112:115], v[16:31]
	ds_read_b128 v[236:239], v95 offset:65056
	v_add_f32_e32 v14, v14, v15
	v_add_f32_e32 v240, v240, v241
	s_waitcnt lgkmcnt(3)
	v_mfma_f32_32x32x16_bf16 v[64:79], v[2:5], v[120:123], v[64:79]
	ds_read_b128 v[2:5], v95 offset:51264
	v_add_f32_e32 v0, v14, v240
	s_waitcnt lgkmcnt(3)
	v_mfma_f32_32x32x16_bf16 v[48:63], v[6:9], v[120:123], v[48:63]
	ds_read_b128 v[6:9], v95 offset:55872
	v_add_f32_e32 v80, v80, v0
	s_waitcnt lgkmcnt(3)
	v_mfma_f32_32x32x16_bf16 v[32:47], v[10:13], v[120:123], v[32:47]
	ds_read_b128 v[10:13], v95 offset:60480
	s_xor_b32 s98, s71, 1
	s_mulk_i32 s98, 0x4800
	v_add_u32_e32 v235, s98, v229
	s_waitcnt vmcnt(0)
	ds_write_b128 v235, v[160:163] offset:51200
	ds_write_b128 v235, v[164:167] offset:51264
	s_waitcnt lgkmcnt(3)
	v_mfma_f32_32x32x16_bf16 v[16:31], v[236:239], v[120:123], v[16:31]
	ds_read_b128 v[236:239], v95 offset:65088
	s_waitcnt lgkmcnt(3)
	v_mfma_f32_32x32x16_bf16 v[64:79], v[2:5], v[96:99], v[64:79]
	ds_read_b128 v[2:5], v95 offset:51296
	s_waitcnt lgkmcnt(3)
	v_mfma_f32_32x32x16_bf16 v[48:63], v[6:9], v[96:99], v[48:63]
	ds_read_b128 v[6:9], v95 offset:55904
	s_waitcnt lgkmcnt(3)
	v_mfma_f32_32x32x16_bf16 v[32:47], v[10:13], v[96:99], v[32:47]
	ds_read_b128 v[10:13], v95 offset:60512
	s_waitcnt lgkmcnt(3)
	v_mfma_f32_32x32x16_bf16 v[16:31], v[236:239], v[96:99], v[16:31]
	ds_read_b128 v[236:239], v95 offset:65120
	s_waitcnt lgkmcnt(3)
	v_mfma_f32_32x32x16_bf16 v[64:79], v[2:5], v[104:107], v[64:79]
	s_waitcnt lgkmcnt(2)
	v_mfma_f32_32x32x16_bf16 v[48:63], v[6:9], v[104:107], v[48:63]
	s_waitcnt lgkmcnt(1)
	v_mfma_f32_32x32x16_bf16 v[32:47], v[10:13], v[104:107], v[32:47]
	s_waitcnt lgkmcnt(0)
	v_mfma_f32_32x32x16_bf16 v[16:31], v[236:239], v[104:107], v[16:31]
	s_or_b64 exec, exec, s[6:7]
	s_branch .LBB0_2597
	s_andn2_b64 vcc, exec, s[26:27]
	s_cbranch_vccz .LBB0_2603

; __global__ void __launch_bounds__(512, 2) trunk_fwd(Params Parg) {
	.amdhsa_kernel _Z9trunk_fwd6Params
		.amdhsa_group_segment_fixed_size 0
		.amdhsa_private_segment_fixed_size 0
		.amdhsa_kernarg_size 416
		.amdhsa_user_sgpr_count 2
		.amdhsa_user_sgpr_dispatch_ptr 0
		.amdhsa_user_sgpr_queue_ptr 0
		.amdhsa_user_sgpr_kernarg_segment_ptr 1
		.amdhsa_user_sgpr_dispatch_id 0
		.amdhsa_user_sgpr_kernarg_preload_length 0
		.amdhsa_user_sgpr_kernarg_preload_offset 0
		.amdhsa_user_sgpr_private_segment_size 0
		.amdhsa_uses_dynamic_stack 0
		.amdhsa_enable_private_segment 0
		.amdhsa_system_sgpr_workgroup_id_x 1
		.amdhsa_system_sgpr_workgroup_id_y 0
		.amdhsa_system_sgpr_workgroup_id_z 0
		.amdhsa_system_sgpr_workgroup_info 0
		.amdhsa_system_vgpr_workitem_id 2
		.amdhsa_next_free_vgpr 255
		.amdhsa_next_free_sgpr 102
		.amdhsa_accum_offset 256
		.amdhsa_reserve_vcc 1
		.amdhsa_float_round_mode_32 0
		.amdhsa_float_round_mode_16_64 0
		.amdhsa_float_denorm_mode_32 3
		.amdhsa_float_denorm_mode_16_64 3
		.amdhsa_dx10_clamp 1
		.amdhsa_ieee_mode 1
		.amdhsa_fp16_overflow 0
		.amdhsa_tg_split 0
		.amdhsa_exception_fp_ieee_invalid_op 0
		.amdhsa_exception_fp_denorm_src 0
		.amdhsa_exception_fp_ieee_div_zero 0
		.amdhsa_exception_fp_ieee_overflow 0
		.amdhsa_exception_fp_ieee_underflow 0
		.amdhsa_exception_fp_ieee_inexact 0
		.amdhsa_exception_int_div_zero 0
	.end_amdhsa_kernel

; __global__ void __launch_bounds__(512, 2) trunk_fwd(Params Parg) {
amdhsa.kernels:
  - .agpr_count:     0
    .args:
      - .offset:         0
        .size:           160
        .value_kind:     by_value
      - .offset:         160
        .size:           4
        .value_kind:     hidden_block_count_x
      - .offset:         164
        .size:           4
        .value_kind:     hidden_block_count_y
      - .offset:         168
        .size:           4
        .value_kind:     hidden_block_count_z
      - .offset:         172
        .size:           2
        .value_kind:     hidden_group_size_x
      - .offset:         174
        .size:           2
        .value_kind:     hidden_group_size_y
      - .offset:         176
        .size:           2
        .value_kind:     hidden_group_size_z
      - .offset:         178
        .size:           2
        .value_kind:     hidden_remainder_x
      - .offset:         180
        .size:           2
        .value_kind:     hidden_remainder_y
      - .offset:         182
        .size:           2
        .value_kind:     hidden_remainder_z
      - .offset:         200
        .size:           8
        .value_kind:     hidden_global_offset_x
      - .offset:         208
        .size:           8
        .value_kind:     hidden_global_offset_y
      - .offset:         216
        .size:           8
        .value_kind:     hidden_global_offset_z
      - .offset:         224
        .size:           2
        .value_kind:     hidden_grid_dims
      - .offset:         248
        .size:           8
        .value_kind:     hidden_multigrid_sync_arg
      - .offset:         280
        .size:           4
        .value_kind:     hidden_dynamic_lds_size
    .group_segment_fixed_size: 0
    .kernarg_segment_align: 8
    .kernarg_segment_size: 416
    .language:       OpenCL C
    .language_version:
      - 2
      - 0
    .max_flat_workgroup_size: 512
    .name:           _Z9trunk_fwd6Params
    .private_segment_fixed_size: 0
    .sgpr_count:     108
    .sgpr_spill_count: 17
    .symbol:         _Z9trunk_fwd6Params.kd
    .uniform_work_group_size: 1
    .uses_dynamic_stack: false
    .vgpr_count:     255
    .vgpr_spill_count: 0
    .wavefront_size: 64
